# mLSTM prompt chunk loop: 8 serialized V-row loads issued together; sample_ml jobs rebalanced 3/5 between SSD-prompt and mLSTM-prompt workgroups
# baseline (speedup 1.0000x reference)
; __device__ __forceinline__ unsigned pack2(float lo, float hi) { unsigned r; asm("v_cvt_pk_bf16_f32 %0, %1, %2" : "=v"(r) : "v"(lo), "v"(hi)); return r; }
; __device__ __forceinline__ float bf_lo(unsigned u) { return __uint_as_float(u << 16); }
; __device__ __forceinline__ float bf_hi(unsigned u) { return __uint_as_float(u & 0xffff0000u); }
; template <bool ML>
; __device__ __forceinline__ void load_block(const Params& p, float (&val)[8][4], int b, int p0, int Lv, int rb, int cg, int colbase, int chbase, float mlscale) {
;     ...
;     if (ML) {
; #pragma unroll
;         for (int r = 0; r < 8; ++r) {
;             const int row = row_of(b, p0 + t0 + r);
;             const u32x2 raw = *(const u32x2*)(U + (size_t)row * N1P + colbase + cg * 4);
;             val[r][0] = bf_lo(raw[0]) * mlscale; val[r][1] = bf_hi(raw[0]) * mlscale; val[r][2] = bf_lo(raw[1]) * mlscale; val[r][3] = bf_hi(raw[1]) * mlscale;
;         }
; __device__ __forceinline__ void store_rows(unsigned char* base, const float (&val)[8][4], int rb, int cg) {
; #pragma unroll
;     for (int r = 0; r < 8; ++r) *(u32x2*)(base + (rb * 8 + r) * RS + cg * 8) = (u32x2){pack2(val[r][0], val[r][1]), pack2(val[r][2], val[r][3])};
; }
; __device__ __forceinline__ void store_cols(unsigned char* base, const float (&val)[8][4], int rb, int cg, const float* scale) {
;     float s[8];
; #pragma unroll
;     for (int r = 0; r < 8; ++r) s[r] = scale ? scale[rb * 8 + r] : 1.f;
; #pragma unroll
;     for (int i = 0; i < 4; ++i) {
;         const int row = cg * 4 + i;
;         u32x4 o; o[0] = pack2(val[0][i] * s[0], val[1][i] * s[1]); o[1] = pack2(val[2][i] * s[2], val[3][i] * s[3]);
;         o[2] = pack2(val[4][i] * s[4], val[5][i] * s[5]); o[3] = pack2(val[6][i] * s[6], val[7][i] * s[7]);
;         *(u32x4*)(base + row * RS + ((rb ^ ((row >> 3) & 7)) << 4)) = o;
;     }
; }
.LBB0_471:
	s_or_b64 exec, exec, s[0:1]
	s_bitcmp1_b32 s44, 0
	s_cselect_b64 s[0:1], -1, 0
	s_and_b64 s[20:21], s[0:1], exec
	s_cselect_b32 s20, 0xc80, 0
	v_cvt_pk_bf16_f32 v58, v32, v33
	v_cvt_pk_bf16_f32 v59, v20, v21
	v_add_u32_e32 v62, 0x8800, v55
	s_add_i32 s48, s20, 0
	v_cvt_pk_bf16_f32 v60, v36, v37
	v_cvt_pk_bf16_f32 v61, v22, v23
	ds_write2_b64 v62, v[58:59], v[60:61] offset1:34
	v_cvt_pk_bf16_f32 v54, v38, v39
	v_cvt_pk_bf16_f32 v55, v24, v25
	v_cvt_pk_bf16_f32 v58, v40, v41
	v_cvt_pk_bf16_f32 v59, v26, v27
	s_add_i32 s48, s48, 0x22000
	ds_write2_b64 v62, v[54:55], v[58:59] offset0:68 offset1:102
	v_cvt_pk_bf16_f32 v54, v42, v43
	v_cvt_pk_bf16_f32 v55, v28, v29
	v_cvt_pk_bf16_f32 v58, v44, v45
	v_cvt_pk_bf16_f32 v59, v30, v31
	ds_write2_b64 v62, v[54:55], v[58:59] offset0:136 offset1:170
	v_cvt_pk_bf16_f32 v54, v46, v47
	v_cvt_pk_bf16_f32 v55, v34, v35
	v_cvt_pk_bf16_f32 v58, v48, v49
	v_cvt_pk_bf16_f32 v59, v57, v56
	ds_write2_b64 v62, v[54:55], v[58:59] offset0:204 offset1:238
	v_lshl_add_u32 v53, v53, 2, s48
	ds_read_b128 v[58:61], v53 offset:2048
	ds_read_b128 v[62:65], v53 offset:2064
	v_lshrrev_b32_e32 v53, 1, v50
	v_bitop3_b32 v52, v53, v52, 7 bitop3:0x6c
	v_lshlrev_b32_e32 v66, 4, v52
	s_waitcnt lgkmcnt(1)
	v_mul_f32_e32 v36, v36, v59
	v_mul_f32_e32 v32, v32, v58
	v_cvt_pk_bf16_f32 v52, v32, v36
	v_mul_f32_e32 v36, v40, v61
	v_mul_f32_e32 v32, v38, v60
	v_cvt_pk_bf16_f32 v53, v32, v36
	s_waitcnt lgkmcnt(0)
	v_mul_f32_e32 v36, v44, v63
	v_mul_f32_e32 v32, v42, v62
	v_cvt_pk_bf16_f32 v54, v32, v36
	v_mul_f32_e32 v36, v48, v65
	v_mul_f32_e32 v32, v46, v64
	v_cvt_pk_bf16_f32 v55, v32, v36
	v_mul_f32_e32 v33, v33, v58
	v_mul_f32_e32 v36, v37, v59
	v_mul_u32_u24_e32 v32, 0x440, v51
	v_cvt_pk_bf16_f32 v36, v33, v36
	v_mul_f32_e32 v33, v39, v60
	v_mul_f32_e32 v37, v41, v61
	v_add3_u32 v32, s51, v66, v32
	v_cvt_pk_bf16_f32 v37, v33, v37
	v_mul_f32_e32 v33, v43, v62
	v_mul_f32_e32 v38, v45, v63
	v_mul_f32_e32 v39, v49, v65
	v_mul_f32_e32 v20, v20, v58
	v_cvt_pk_bf16_f32 v38, v33, v38
	v_mul_f32_e32 v33, v47, v64
	v_cvt_pk_bf16_f32 v39, v33, v39
	ds_write_b128 v32, v[36:39] offset:272
	v_mul_f32_e32 v22, v22, v59
	v_cvt_pk_bf16_f32 v36, v20, v22
	v_mul_f32_e32 v20, v24, v60
	v_mul_f32_e32 v22, v26, v61
	v_cvt_pk_bf16_f32 v37, v20, v22
	v_mul_f32_e32 v20, v28, v62
	v_mul_f32_e32 v22, v30, v63
	v_cvt_pk_bf16_f32 v38, v20, v22
	v_mul_f32_e32 v20, v34, v64
	v_mul_f32_e32 v22, v57, v65
	v_cvt_pk_bf16_f32 v39, v20, v22
	v_mul_f32_e32 v20, v21, v58
	v_mul_f32_e32 v21, v23, v59
	v_cvt_pk_bf16_f32 v20, v20, v21
	v_mul_f32_e32 v21, v25, v60
	v_mul_f32_e32 v22, v27, v61
	v_cvt_pk_bf16_f32 v21, v21, v22
	v_mul_f32_e32 v22, v29, v62
	v_mul_f32_e32 v23, v31, v63
	v_and_b32_e32 v137, 15, v50
	v_cvt_pk_bf16_f32 v22, v22, v23
	v_mul_f32_e32 v23, v35, v64
	ds_write_b128 v32, v[52:55]
	ds_write_b128 v32, v[36:39] offset:544
	v_mul_f32_e32 v24, v56, v65
	v_cvt_pk_bf16_f32 v23, v23, v24
	ds_write_b128 v32, v[20:23] offset:816
	s_movk_i32 s20, 0x100
	v_cmp_gt_i32_e32 vcc, s20, v50
	s_and_saveexec_b64 s[20:21], vcc
	s_cbranch_execz .LBB0_477
	v_ashrrev_i32_e32 v21, 4, v50
	v_lshlrev_b32_e32 v54, 3, v21
	v_cmp_le_i32_e32 vcc, s43, v54
	s_and_saveexec_b64 s[40:41], vcc
	s_xor_b64 s[40:41], exec, s[40:41]
	s_or_saveexec_b64 s[40:41], s[40:41]
	v_mov_b32_e32 v49, 0
	v_mov_b32_e32 v26, 0
	v_mov_b32_e32 v24, 0
	v_mov_b32_e32 v22, 0
	v_mov_b32_e32 v20, 0
	v_mov_b32_e32 v30, 0
	v_mov_b32_e32 v28, 0
	v_mov_b32_e32 v25, 0
	v_mov_b32_e32 v23, 0
	v_mov_b32_e32 v33, 0
	v_mov_b32_e32 v31, 0
	v_mov_b32_e32 v29, 0
	v_mov_b32_e32 v27, 0
	v_mov_b32_e32 v38, 0
	v_mov_b32_e32 v36, 0
	v_mov_b32_e32 v34, 0
	v_mov_b32_e32 v32, 0
	v_mov_b32_e32 v41, 0
	v_mov_b32_e32 v39, 0
	v_mov_b32_e32 v37, 0
	v_mov_b32_e32 v35, 0
	v_mov_b32_e32 v46, 0
	v_mov_b32_e32 v44, 0
	v_mov_b32_e32 v42, 0
	v_mov_b32_e32 v40, 0
	v_mov_b32_e32 v48, 0
	v_mov_b32_e32 v47, 0
	v_mov_b32_e32 v45, 0
	v_mov_b32_e32 v43, 0
	v_mov_b32_e32 v53, 0
	v_mov_b32_e32 v52, 0
	v_mov_b32_e32 v51, 0
	s_xor_b64 exec, exec, s[40:41]
	s_cbranch_execz .LBB0_476
	v_add_u32_e32 v51, s42, v54
	v_mov_b32_e32 v56, s54
	v_mov_b32_e32 v57, s96
	v_lshlrev_b32_e32 v148, 3, v137
	v_lshl_add_u64 v[52:53], s[4:5], 0, v[148:149]
	v_cmp_gt_i32_e32 vcc, 16, v51
	v_cndmask_b32_e32 v20, v56, v57, vcc
	v_add_u32_e32 v20, v20, v51
	v_mad_i64_i32 v[190:191], vcc, v20, s45, v[52:53]
	global_load_dwordx2 v[190:191], v[190:191], off
	v_cmp_gt_i32_e32 vcc, 15, v51
	v_cndmask_b32_e32 v20, v56, v57, vcc
	v_add3_u32 v20, v20, v51, 1
	v_mad_i64_i32 v[192:193], vcc, v20, s45, v[52:53]
	global_load_dwordx2 v[192:193], v[192:193], off
	v_cmp_gt_i32_e32 vcc, 14, v51
	v_cndmask_b32_e32 v20, v56, v57, vcc
	v_add3_u32 v20, v20, v51, 2
	v_mad_i64_i32 v[194:195], vcc, v20, s45, v[52:53]
	global_load_dwordx2 v[194:195], v[194:195], off
	v_cmp_gt_i32_e32 vcc, 13, v51
	v_cndmask_b32_e32 v20, v56, v57, vcc
	v_add3_u32 v20, v20, v51, 3
	v_mad_i64_i32 v[196:197], vcc, v20, s45, v[52:53]
	global_load_dwordx2 v[196:197], v[196:197], off
	v_cmp_gt_i32_e32 vcc, 12, v51
	v_cndmask_b32_e32 v20, v56, v57, vcc
	v_add3_u32 v20, v20, v51, 4
	v_mad_i64_i32 v[198:199], vcc, v20, s45, v[52:53]
	global_load_dwordx2 v[198:199], v[198:199], off
	v_cmp_gt_i32_e32 vcc, 11, v51
	v_cndmask_b32_e32 v20, v56, v57, vcc
	v_add3_u32 v20, v20, v51, 5
	v_mad_i64_i32 v[200:201], vcc, v20, s45, v[52:53]
	global_load_dwordx2 v[200:201], v[200:201], off
	v_cmp_gt_i32_e32 vcc, 10, v51
	v_cndmask_b32_e32 v20, v56, v57, vcc
	v_add3_u32 v20, v20, v51, 6
	v_mad_i64_i32 v[54:55], vcc, v20, s45, v[52:53]
	global_load_dwordx2 v[54:55], v[54:55], off
	v_cmp_gt_i32_e32 vcc, 9, v51
	v_cndmask_b32_e32 v20, v56, v57, vcc
	v_add3_u32 v20, v20, v51, 7
	v_mad_i64_i32 v[52:53], vcc, v20, s45, v[52:53]
	global_load_dwordx2 v[52:53], v[52:53], off
	s_waitcnt vmcnt(7)
	v_lshlrev_b32_e32 v22, 16, v191
	v_and_b32_e32 v20, 0xffff0000, v191
	v_lshlrev_b32_e32 v26, 16, v190
	v_and_b32_e32 v24, 0xffff0000, v190
	s_waitcnt vmcnt(6)
	v_lshlrev_b32_e32 v25, 16, v193
	v_and_b32_e32 v23, 0xffff0000, v193
	v_lshlrev_b32_e32 v30, 16, v192
	v_and_b32_e32 v28, 0xffff0000, v192
	s_waitcnt vmcnt(5)
	v_lshlrev_b32_e32 v29, 16, v195
	v_and_b32_e32 v27, 0xffff0000, v195
	v_lshlrev_b32_e32 v33, 16, v194
	v_and_b32_e32 v31, 0xffff0000, v194
	s_waitcnt vmcnt(4)
	v_lshlrev_b32_e32 v34, 16, v197
	v_and_b32_e32 v32, 0xffff0000, v197
	v_lshlrev_b32_e32 v38, 16, v196
	v_and_b32_e32 v36, 0xffff0000, v196
	s_waitcnt vmcnt(3)
	v_lshlrev_b32_e32 v37, 16, v199
	v_and_b32_e32 v35, 0xffff0000, v199
	v_lshlrev_b32_e32 v41, 16, v198
	v_and_b32_e32 v39, 0xffff0000, v198
	s_waitcnt vmcnt(2)
	v_lshlrev_b32_e32 v42, 16, v201
	v_and_b32_e32 v40, 0xffff0000, v201
	v_lshlrev_b32_e32 v46, 16, v200
	v_and_b32_e32 v44, 0xffff0000, v200
	s_waitcnt vmcnt(1)
	v_lshlrev_b32_e32 v45, 16, v55
	v_and_b32_e32 v43, 0xffff0000, v55
	v_lshlrev_b32_e32 v48, 16, v54
	v_and_b32_e32 v47, 0xffff0000, v54
	s_waitcnt vmcnt(0)
	v_lshlrev_b32_e32 v51, 16, v53
	v_and_b32_e32 v49, 0xffff0000, v53
	v_lshlrev_b32_e32 v53, 16, v52
	v_and_b32_e32 v52, 0xffff0000, v52

; __device__ __forceinline__ int opaque_bid() { int t = blockIdx.x; asm volatile("" : "+s"(t)); return t; }
; __device__ __forceinline__ void phase_scan(const Params& p, unsigned char* smem) {
;     ...
;     for (int j = opaque_bid(); j < 256; j += gridDim.x) { if (j < 128) { if (SC_MASK & 1) prompt_scan<false>(p, smem, j); } else { if (SC_MASK & 2) prompt_scan<true>(p, smem, j - 128); } }
;     if (SC_MASK & 4) for (int j = opaque_bid(); j < 256; j += gridDim.x) sample_ssd(p, smem, j);
;     if (SC_MASK & 8) for (int j = opaque_bid(); j < 1024; j += gridDim.x) sample_ml(p, smem, j);
.LBB0_714:
	s_or_b64 exec, exec, s[4:5]
	v_readlane_b32 s0, v254, 31
	s_add_i32 s2, s2, s0
	s_waitcnt lgkmcnt(0)
	s_barrier
	s_sub_u32 s0, s2, 0x300
	s_cmpk_lt_u32 s0, 0x80
	s_cbranch_scc1 .LBB0_747
	s_sub_u32 s0, s2, 0x480
	s_cmpk_lt_u32 s0, 0x80
	s_cbranch_scc0 .Lsml_norm
	s_add_u32 s2, s0, 0x300
	s_branch .LBB0_715
.Lsml_norm:
	s_cmpk_gt_i32 s2, 0x3ff
	s_cbranch_scc1 .LBB0_747
